# FFN-down LN epilogue: 32 serialized residual-row loads -> 11-deep counted-vmcnt pipeline
# baseline (speedup 1.0000x reference)
.LBB0_536:
	s_lshl_b32 s0, s21, 5
	s_lshl_b32 s1, s62, 2
	s_add_u32 s8, s56, s1
	s_addc_u32 s9, s57, 0
	s_lshl_b32 s1, s60, 8
	s_or_b32 s0, s1, s0
	v_lshrrev_b32_e32 v130, 2, v166
	v_and_or_b32 v160, v130, 12, s0
	s_ashr_i32 s0, s19, 31
	s_lshr_b32 s0, s0, 28
	s_add_i32 s0, s19, s0
	s_ashr_i32 s0, s0, 4
	s_mul_hi_i32 s1, s0, 0x2400
	s_mulk_i32 s0, 0x2400
	s_lshl_b32 s24, s19, 8
	s_lshl_b64 s[62:63], s[0:1], 2
	s_add_u32 s0, s8, s62
	v_ashrrev_i32_e32 v161, 31, v160
	s_addc_u32 s1, s9, s63
	v_lshlrev_b64 v[142:143], 2, v[160:161]
	v_lshl_add_u64 v[130:131], s[0:1], 0, v[142:143]
	s_mov_b64 s[0:1], 0x100000
	v_lshl_add_u64 v[148:149], v[130:131], 0, s[0:1]
	s_mov_b32 s0, 0x100000
	v_add_co_u32_e32 v130, vcc, s0, v130
	s_barrier
	s_nop 0
	v_addc_co_u32_e32 v131, vcc, 0, v131, vcc
	global_load_dwordx4 v[132:135], v[130:131], off
	global_load_dwordx4 v[136:139], v[148:149], off offset:64
	global_load_dwordx4 v[210:213], v[148:149], off offset:512
	global_load_dwordx4 v[216:219], v[148:149], off offset:576
	s_add_i32 s0, s24, s35
	v_and_b32_e32 v168, 63, v166
	v_or_b32_e32 v144, s0, v167
	v_or_b32_e32 v146, 16, v144
	v_or_b32_e32 v148, 32, v144
	v_or_b32_e32 v150, 48, v144
	v_add_u32_e32 v152, 0x80, v144
	v_add_u32_e32 v154, 0x90, v144
	v_add_u32_e32 v156, 0xa0, v144
	v_add_u32_e32 v158, 0xb0, v144
	v_ashrrev_i32_e32 v145, 31, v144
	v_ashrrev_i32_e32 v147, 31, v146
	v_ashrrev_i32_e32 v149, 31, v148
	v_ashrrev_i32_e32 v151, 31, v150
	v_ashrrev_i32_e32 v153, 31, v152
	v_ashrrev_i32_e32 v155, 31, v154
	v_ashrrev_i32_e32 v157, 31, v156
	v_ashrrev_i32_e32 v159, 31, v158
	s_mov_b32 s0, 0x3f9837f0
	v_lshlrev_b64 v[248:249], 12, v[144:145]
	v_lshl_add_u64 v[248:249], s[64:65], 0, v[248:249]
	v_lshl_add_u64 v[248:249], v[248:249], 0, v[142:143]
	global_load_dwordx4 v[170:173], v[248:249], off
	global_load_dwordx4 v[174:177], v[248:249], off offset:64
	global_load_dwordx4 v[178:181], v[248:249], off offset:512
	global_load_dwordx4 v[182:185], v[248:249], off offset:576
	v_lshlrev_b64 v[248:249], 12, v[146:147]
	v_lshl_add_u64 v[248:249], s[64:65], 0, v[248:249]
	v_lshl_add_u64 v[248:249], v[248:249], 0, v[142:143]
	global_load_dwordx4 v[202:205], v[248:249], off
	global_load_dwordx4 v[206:209], v[248:249], off offset:64
	global_load_dwordx4 v[226:229], v[248:249], off offset:512
	global_load_dwordx4 v[230:233], v[248:249], off offset:576
	v_lshlrev_b64 v[248:249], 12, v[148:149]
	v_lshl_add_u64 v[248:249], s[64:65], 0, v[248:249]
	v_lshl_add_u64 v[248:249], v[248:249], 0, v[142:143]
	global_load_dwordx4 v[234:237], v[248:249], off
	global_load_dwordx4 v[238:241], v[248:249], off offset:64
	global_load_dwordx4 v[242:245], v[248:249], off offset:512
	s_waitcnt vmcnt(11)
	v_pk_mul_f32 v[130:131], v[134:135], 0.5 op_sel_hi:[1,0]
	v_pk_mul_f32 v[134:135], v[138:139], 0.5 op_sel_hi:[1,0]
	v_pk_mul_f32 v[138:139], v[212:213], 0.5 op_sel_hi:[1,0]
	v_pk_mul_f32 v[140:141], v[210:211], 0.5 op_sel_hi:[1,0]
	v_pk_mul_f32 v[132:133], v[132:133], 0.5 op_sel_hi:[1,0]
	v_pk_mul_f32 v[136:137], v[136:137], 0.5 op_sel_hi:[1,0]
	v_pk_mul_f32 v[164:165], v[216:217], 0.5 op_sel_hi:[1,0]
	v_pk_mul_f32 v[162:163], v[218:219], 0.5 op_sel_hi:[1,0]
	s_waitcnt vmcnt(10)
	v_pk_mul_f32 v[172:173], v[172:173], s[0:1] op_sel_hi:[1,0]
	v_pk_mul_f32 v[170:171], v[170:171], s[0:1] op_sel_hi:[1,0]
	v_pk_fma_f32 v[68:69], v[68:69], v[130:131], v[172:173]
	v_pk_fma_f32 v[66:67], v[66:67], v[132:133], v[170:171]
	global_load_dwordx4 v[170:173], v[248:249], off offset:576
	s_waitcnt vmcnt(10)
	v_pk_mul_f32 v[176:177], v[176:177], s[0:1] op_sel_hi:[1,0]
	v_pk_mul_f32 v[174:175], v[174:175], s[0:1] op_sel_hi:[1,0]
	v_pk_fma_f32 v[36:37], v[36:37], v[134:135], v[176:177]
	v_pk_fma_f32 v[34:35], v[34:35], v[136:137], v[174:175]
	v_lshlrev_b64 v[248:249], 12, v[150:151]
	v_lshl_add_u64 v[248:249], s[64:65], 0, v[248:249]
	v_lshl_add_u64 v[248:249], v[248:249], 0, v[142:143]
	global_load_dwordx4 v[174:177], v[248:249], off
	s_waitcnt vmcnt(10)
	v_pk_mul_f32 v[180:181], v[180:181], s[0:1] op_sel_hi:[1,0]
	v_pk_mul_f32 v[178:179], v[178:179], s[0:1] op_sel_hi:[1,0]
	v_pk_fma_f32 v[16:17], v[16:17], v[138:139], v[180:181]
	v_pk_fma_f32 v[14:15], v[14:15], v[140:141], v[178:179]
	global_load_dwordx4 v[178:181], v[248:249], off offset:64
	s_waitcnt vmcnt(10)
	v_pk_mul_f32 v[184:185], v[184:185], s[0:1] op_sel_hi:[1,0]
	v_pk_mul_f32 v[182:183], v[182:183], s[0:1] op_sel_hi:[1,0]
	v_pk_fma_f32 v[4:5], v[4:5], v[162:163], v[184:185]
	v_pk_fma_f32 v[2:3], v[2:3], v[164:165], v[182:183]
	global_load_dwordx4 v[182:185], v[248:249], off offset:512
	s_waitcnt vmcnt(10)
	v_pk_mul_f32 v[204:205], v[204:205], s[0:1] op_sel_hi:[1,0]
	v_pk_mul_f32 v[202:203], v[202:203], s[0:1] op_sel_hi:[1,0]
	v_pk_fma_f32 v[80:81], v[80:81], v[130:131], v[204:205]
	v_pk_fma_f32 v[78:79], v[78:79], v[132:133], v[202:203]
	global_load_dwordx4 v[202:205], v[248:249], off offset:576
	s_waitcnt vmcnt(10)
	v_pk_mul_f32 v[208:209], v[208:209], s[0:1] op_sel_hi:[1,0]
	v_pk_mul_f32 v[206:207], v[206:207], s[0:1] op_sel_hi:[1,0]
	v_pk_fma_f32 v[48:49], v[48:49], v[134:135], v[208:209]
	v_pk_fma_f32 v[46:47], v[46:47], v[136:137], v[206:207]
	v_lshlrev_b64 v[248:249], 12, v[152:153]
	v_lshl_add_u64 v[248:249], s[64:65], 0, v[248:249]
	v_lshl_add_u64 v[248:249], v[248:249], 0, v[142:143]
	global_load_dwordx4 v[206:209], v[248:249], off
	s_waitcnt vmcnt(10)
	v_pk_mul_f32 v[228:229], v[228:229], s[0:1] op_sel_hi:[1,0]
	v_pk_mul_f32 v[226:227], v[226:227], s[0:1] op_sel_hi:[1,0]
	v_pk_fma_f32 v[24:25], v[24:25], v[138:139], v[228:229]
	v_pk_fma_f32 v[22:23], v[22:23], v[140:141], v[226:227]
	global_load_dwordx4 v[226:229], v[248:249], off offset:64
	s_waitcnt vmcnt(10)
	v_pk_mul_f32 v[232:233], v[232:233], s[0:1] op_sel_hi:[1,0]
	v_pk_mul_f32 v[230:231], v[230:231], s[0:1] op_sel_hi:[1,0]
	v_pk_fma_f32 v[8:9], v[8:9], v[162:163], v[232:233]
	v_pk_fma_f32 v[6:7], v[6:7], v[164:165], v[230:231]
	global_load_dwordx4 v[230:233], v[248:249], off offset:512
	s_waitcnt vmcnt(10)
	v_pk_mul_f32 v[236:237], v[236:237], s[0:1] op_sel_hi:[1,0]
	v_pk_mul_f32 v[234:235], v[234:235], s[0:1] op_sel_hi:[1,0]
	v_pk_fma_f32 v[108:109], v[108:109], v[130:131], v[236:237]
	v_pk_fma_f32 v[106:107], v[106:107], v[132:133], v[234:235]
	global_load_dwordx4 v[234:237], v[248:249], off offset:576
	s_waitcnt vmcnt(10)
	v_pk_mul_f32 v[240:241], v[240:241], s[0:1] op_sel_hi:[1,0]
	v_pk_mul_f32 v[238:239], v[238:239], s[0:1] op_sel_hi:[1,0]
	v_pk_fma_f32 v[64:65], v[64:65], v[134:135], v[240:241]
	v_pk_fma_f32 v[62:63], v[62:63], v[136:137], v[238:239]
	v_lshlrev_b64 v[248:249], 12, v[154:155]
	v_lshl_add_u64 v[248:249], s[64:65], 0, v[248:249]
	v_lshl_add_u64 v[248:249], v[248:249], 0, v[142:143]
	global_load_dwordx4 v[238:241], v[248:249], off
	s_waitcnt vmcnt(10)
	v_pk_mul_f32 v[244:245], v[244:245], s[0:1] op_sel_hi:[1,0]
	v_pk_mul_f32 v[242:243], v[242:243], s[0:1] op_sel_hi:[1,0]
	v_pk_fma_f32 v[32:33], v[32:33], v[138:139], v[244:245]
	v_pk_fma_f32 v[30:31], v[30:31], v[140:141], v[242:243]
	global_load_dwordx4 v[242:245], v[248:249], off offset:64
	s_waitcnt vmcnt(10)
	v_pk_mul_f32 v[172:173], v[172:173], s[0:1] op_sel_hi:[1,0]
	v_pk_mul_f32 v[170:171], v[170:171], s[0:1] op_sel_hi:[1,0]
	v_pk_fma_f32 v[12:13], v[12:13], v[162:163], v[172:173]
	v_pk_fma_f32 v[10:11], v[10:11], v[164:165], v[170:171]
	global_load_dwordx4 v[170:173], v[248:249], off offset:512
	s_waitcnt vmcnt(10)
	v_pk_mul_f32 v[176:177], v[176:177], s[0:1] op_sel_hi:[1,0]
	v_pk_mul_f32 v[174:175], v[174:175], s[0:1] op_sel_hi:[1,0]
	v_pk_fma_f32 v[120:121], v[120:121], v[130:131], v[176:177]
	v_pk_fma_f32 v[118:119], v[118:119], v[132:133], v[174:175]
	global_load_dwordx4 v[174:177], v[248:249], off offset:576
	s_waitcnt vmcnt(10)
	v_pk_mul_f32 v[180:181], v[180:181], s[0:1] op_sel_hi:[1,0]
	v_pk_mul_f32 v[178:179], v[178:179], s[0:1] op_sel_hi:[1,0]
	v_pk_fma_f32 v[76:77], v[76:77], v[134:135], v[180:181]
	v_pk_fma_f32 v[74:75], v[74:75], v[136:137], v[178:179]
	v_lshlrev_b64 v[248:249], 12, v[156:157]
	v_lshl_add_u64 v[248:249], s[64:65], 0, v[248:249]
	v_lshl_add_u64 v[248:249], v[248:249], 0, v[142:143]
	global_load_dwordx4 v[178:181], v[248:249], off
	s_waitcnt vmcnt(10)
	v_pk_mul_f32 v[184:185], v[184:185], s[0:1] op_sel_hi:[1,0]
	v_pk_mul_f32 v[182:183], v[182:183], s[0:1] op_sel_hi:[1,0]
	v_pk_fma_f32 v[44:45], v[44:45], v[138:139], v[184:185]
	v_pk_fma_f32 v[42:43], v[42:43], v[140:141], v[182:183]
	global_load_dwordx4 v[182:185], v[248:249], off offset:64
	s_waitcnt vmcnt(10)
	v_pk_mul_f32 v[204:205], v[204:205], s[0:1] op_sel_hi:[1,0]
	v_pk_mul_f32 v[202:203], v[202:203], s[0:1] op_sel_hi:[1,0]
	v_pk_fma_f32 v[20:21], v[20:21], v[162:163], v[204:205]
	v_pk_fma_f32 v[18:19], v[18:19], v[164:165], v[202:203]
	global_load_dwordx4 v[202:205], v[248:249], off offset:512
	s_waitcnt vmcnt(10)
	v_pk_mul_f32 v[208:209], v[208:209], s[0:1] op_sel_hi:[1,0]
	v_pk_mul_f32 v[206:207], v[206:207], s[0:1] op_sel_hi:[1,0]
	v_pk_fma_f32 v[128:129], v[128:129], v[130:131], v[208:209]
	v_pk_fma_f32 v[126:127], v[126:127], v[132:133], v[206:207]
	global_load_dwordx4 v[206:209], v[248:249], off offset:576
	s_waitcnt vmcnt(10)
	v_pk_mul_f32 v[228:229], v[228:229], s[0:1] op_sel_hi:[1,0]
	v_pk_mul_f32 v[226:227], v[226:227], s[0:1] op_sel_hi:[1,0]
	v_pk_fma_f32 v[100:101], v[100:101], v[134:135], v[228:229]
	v_pk_fma_f32 v[98:99], v[98:99], v[136:137], v[226:227]
	v_lshlrev_b64 v[248:249], 12, v[158:159]
	v_lshl_add_u64 v[248:249], s[64:65], 0, v[248:249]
	v_lshl_add_u64 v[248:249], v[248:249], 0, v[142:143]
	global_load_dwordx4 v[226:229], v[248:249], off
	s_waitcnt vmcnt(10)
	v_pk_mul_f32 v[232:233], v[232:233], s[0:1] op_sel_hi:[1,0]
	v_pk_mul_f32 v[230:231], v[230:231], s[0:1] op_sel_hi:[1,0]
	v_pk_fma_f32 v[60:61], v[60:61], v[138:139], v[232:233]
	v_pk_fma_f32 v[58:59], v[58:59], v[140:141], v[230:231]
	global_load_dwordx4 v[230:233], v[248:249], off offset:64
	s_waitcnt vmcnt(10)
	v_pk_mul_f32 v[236:237], v[236:237], s[0:1] op_sel_hi:[1,0]
	v_pk_mul_f32 v[234:235], v[234:235], s[0:1] op_sel_hi:[1,0]
	v_pk_fma_f32 v[28:29], v[28:29], v[162:163], v[236:237]
	v_pk_fma_f32 v[26:27], v[26:27], v[164:165], v[234:235]
	global_load_dwordx4 v[234:237], v[248:249], off offset:512
	s_waitcnt vmcnt(10)
	v_pk_mul_f32 v[240:241], v[240:241], s[0:1] op_sel_hi:[1,0]
	v_pk_mul_f32 v[238:239], v[238:239], s[0:1] op_sel_hi:[1,0]
	v_pk_fma_f32 v[124:125], v[124:125], v[130:131], v[240:241]
	v_pk_fma_f32 v[122:123], v[122:123], v[132:133], v[238:239]
	global_load_dwordx4 v[238:241], v[248:249], off offset:576
	s_waitcnt vmcnt(10)
	v_pk_mul_f32 v[244:245], v[244:245], s[0:1] op_sel_hi:[1,0]
	v_pk_mul_f32 v[242:243], v[242:243], s[0:1] op_sel_hi:[1,0]
	v_pk_fma_f32 v[116:117], v[116:117], v[134:135], v[244:245]
	v_pk_fma_f32 v[114:115], v[114:115], v[136:137], v[242:243]
	s_waitcnt vmcnt(9)
	v_pk_mul_f32 v[172:173], v[172:173], s[0:1] op_sel_hi:[1,0]
	v_pk_mul_f32 v[170:171], v[170:171], s[0:1] op_sel_hi:[1,0]
	v_pk_fma_f32 v[72:73], v[72:73], v[138:139], v[172:173]
	v_pk_fma_f32 v[70:71], v[70:71], v[140:141], v[170:171]
	s_waitcnt vmcnt(8)
	v_pk_mul_f32 v[176:177], v[176:177], s[0:1] op_sel_hi:[1,0]
	v_pk_mul_f32 v[174:175], v[174:175], s[0:1] op_sel_hi:[1,0]
	v_pk_fma_f32 v[40:41], v[40:41], v[162:163], v[176:177]
	v_pk_fma_f32 v[38:39], v[38:39], v[164:165], v[174:175]
	s_waitcnt vmcnt(7)
	v_pk_mul_f32 v[180:181], v[180:181], s[0:1] op_sel_hi:[1,0]
	v_pk_mul_f32 v[178:179], v[178:179], s[0:1] op_sel_hi:[1,0]
	v_pk_fma_f32 v[112:113], v[112:113], v[130:131], v[180:181]
	v_pk_fma_f32 v[110:111], v[110:111], v[132:133], v[178:179]
	s_waitcnt vmcnt(6)
	v_pk_mul_f32 v[184:185], v[184:185], s[0:1] op_sel_hi:[1,0]
	v_pk_mul_f32 v[182:183], v[182:183], s[0:1] op_sel_hi:[1,0]
	v_pk_fma_f32 v[104:105], v[104:105], v[134:135], v[184:185]
	v_pk_fma_f32 v[102:103], v[102:103], v[136:137], v[182:183]
	s_waitcnt vmcnt(5)
	v_pk_mul_f32 v[204:205], v[204:205], s[0:1] op_sel_hi:[1,0]
	v_pk_mul_f32 v[202:203], v[202:203], s[0:1] op_sel_hi:[1,0]
	v_pk_fma_f32 v[88:89], v[88:89], v[138:139], v[204:205]
	v_pk_fma_f32 v[86:87], v[86:87], v[140:141], v[202:203]
	s_waitcnt vmcnt(4)
	v_pk_mul_f32 v[208:209], v[208:209], s[0:1] op_sel_hi:[1,0]
	v_pk_mul_f32 v[206:207], v[206:207], s[0:1] op_sel_hi:[1,0]
	v_pk_fma_f32 v[56:57], v[56:57], v[162:163], v[208:209]
	v_pk_fma_f32 v[54:55], v[54:55], v[164:165], v[206:207]
	s_waitcnt vmcnt(3)
	v_pk_mul_f32 v[228:229], v[228:229], s[0:1] op_sel_hi:[1,0]
	v_pk_mul_f32 v[226:227], v[226:227], s[0:1] op_sel_hi:[1,0]
	v_pk_fma_f32 v[96:97], v[96:97], v[130:131], v[228:229]
	v_pk_fma_f32 v[94:95], v[94:95], v[132:133], v[226:227]
	s_waitcnt vmcnt(2)
	v_pk_mul_f32 v[232:233], v[232:233], s[0:1] op_sel_hi:[1,0]
	v_pk_mul_f32 v[230:231], v[230:231], s[0:1] op_sel_hi:[1,0]
	v_pk_fma_f32 v[92:93], v[92:93], v[134:135], v[232:233]
	v_pk_fma_f32 v[90:91], v[90:91], v[136:137], v[230:231]
	s_waitcnt vmcnt(1)
	v_pk_mul_f32 v[236:237], v[236:237], s[0:1] op_sel_hi:[1,0]
	v_pk_mul_f32 v[234:235], v[234:235], s[0:1] op_sel_hi:[1,0]
	v_pk_fma_f32 v[84:85], v[84:85], v[138:139], v[236:237]
	v_pk_fma_f32 v[82:83], v[82:83], v[140:141], v[234:235]
	s_waitcnt vmcnt(0)
	v_pk_mul_f32 v[240:241], v[240:241], s[0:1] op_sel_hi:[1,0]
	v_pk_mul_f32 v[238:239], v[238:239], s[0:1] op_sel_hi:[1,0]
	v_pk_fma_f32 v[52:53], v[52:53], v[162:163], v[240:241]
	v_pk_fma_f32 v[50:51], v[50:51], v[164:165], v[238:239]
	v_mov_b32_e32 v134, v66
	v_mov_b32_e32 v135, v69
	v_mov_b32_e32 v136, v34
	v_mov_b32_e32 v137, v37
	v_add_f32_e32 v139, v16, v17
	v_mov_b32_e32 v138, v3
	v_and_b32_e32 v131, 64, v220
	v_xor_b32_e32 v130, 16, v220
	v_add_u32_e32 v131, 64, v131
	v_cmp_lt_i32_e32 vcc, v130, v131
	v_xor_b32_e32 v132, 32, v220
	v_mov_b32_e32 v133, v68
	v_cndmask_b32_e32 v130, v220, v130, vcc
	v_cmp_lt_i32_e32 vcc, v132, v131
	v_lshlrev_b32_e32 v130, 2, v130
	s_lshl_b32 s0, s21, 3
	v_cndmask_b32_e32 v131, v220, v132, vcc
	v_mov_b32_e32 v132, v67
	v_pk_add_f32 v[132:133], v[132:133], v[134:135]
	v_mov_b32_e32 v134, v35
	v_mov_b32_e32 v135, v36
	v_pk_add_f32 v[134:135], v[134:135], v[136:137]
	v_add_f32_e32 v132, v132, v133
	v_pk_add_f32 v[134:135], v[134:135], v[134:135] op_sel_hi:[0,1]
	v_add_f32_e32 v133, 0, v132
	v_add_f32_e32 v137, v14, v15
	v_mov_b32_e32 v136, v2
	v_mov_b32_e32 v134, v4
	v_mov_b32_e32 v132, v5
	v_pk_add_f32 v[136:137], v[136:137], v[138:139]
	v_pk_add_f32 v[132:133], v[134:135], v[132:133]
	v_lshlrev_b32_e32 v131, 2, v131
	v_pk_add_f32 v[132:133], v[136:137], v[132:133]
	v_cmp_gt_u32_e32 vcc, 16, v168
	v_add_f32_e32 v132, v132, v133
	ds_bpermute_b32 v133, v130, v132
	s_add_i32 s8, s0, 0
	s_waitcnt lgkmcnt(0)
	v_add_f32_e32 v132, v132, v133
	ds_bpermute_b32 v133, v131, v132
	s_waitcnt lgkmcnt(0)
	v_add_f32_e32 v132, v132, v133
	v_fmamk_f32 v134, v132, 0xbc800000, v69
	v_fmamk_f32 v136, v132, 0xbc800000, v67
	v_fmamk_f32 v133, v132, 0xbc800000, v68
	v_fmamk_f32 v135, v132, 0xbc800000, v66
	v_mul_f32_e32 v136, v136, v136
	v_mul_f32_e32 v134, v134, v134
	v_fmac_f32_e32 v136, v135, v135
	v_fmac_f32_e32 v134, v133, v133
	v_fmamk_f32 v135, v132, 0xbc800000, v37
	v_fmamk_f32 v137, v132, 0xbc800000, v35
	v_add_f32_e32 v133, v136, v134
	v_fmamk_f32 v134, v132, 0xbc800000, v36
	v_fmamk_f32 v136, v132, 0xbc800000, v34
	v_mul_f32_e32 v137, v137, v137
	v_mul_f32_e32 v135, v135, v135
	v_fmac_f32_e32 v137, v136, v136
	v_fmac_f32_e32 v135, v134, v134
	v_add_f32_e32 v134, v137, v135
	v_fmamk_f32 v135, v132, 0xbc800000, v17
	v_fmamk_f32 v137, v132, 0xbc800000, v15
	v_add_f32_e32 v133, v133, v134
	v_fmamk_f32 v134, v132, 0xbc800000, v16
	v_fmamk_f32 v136, v132, 0xbc800000, v14
	v_mul_f32_e32 v137, v137, v137
	v_mul_f32_e32 v135, v135, v135
	v_fmac_f32_e32 v137, v136, v136
	v_fmac_f32_e32 v135, v134, v134
	v_add_f32_e32 v134, v137, v135
	v_fmamk_f32 v135, v132, 0xbc800000, v5
	v_fmamk_f32 v137, v132, 0xbc800000, v3
	v_add_f32_e32 v133, v134, v133
	v_fmamk_f32 v134, v132, 0xbc800000, v4
	v_fmamk_f32 v136, v132, 0xbc800000, v2
	v_mul_f32_e32 v137, v137, v137
	v_mul_f32_e32 v135, v135, v135
	v_fmac_f32_e32 v137, v136, v136
	v_fmac_f32_e32 v135, v134, v134
	v_add_f32_e32 v134, v137, v135
	v_add_f32_e32 v133, v134, v133
	ds_bpermute_b32 v134, v130, v133
	s_waitcnt lgkmcnt(0)
	v_add_f32_e32 v133, v133, v134
	ds_bpermute_b32 v134, v131, v133
	s_and_saveexec_b64 s[0:1], vcc
	v_readlane_b32 s61, v251, 36
	s_mov_b64 s[70:71], 0x20000
	s_cbranch_execz .LBB0_538
	s_lshl_b32 s9, s20, 11
	s_add_i32 s9, s8, s9
	v_mul_f32_e32 v132, 0x3c800000, v132
	v_lshl_add_u32 v135, v167, 5, s9
	s_waitcnt lgkmcnt(0)
	v_add_f32_e32 v133, v133, v134
	ds_write_b64 v135, v[132:133]
